# v91 + gather sub-phase B processes two tokens per iteration (two independent load-gather-compute chains in flight)
# speedup vs baseline: 1.0001x; 1.0001x over previous
.Lgy_Btok_8:
	s_mov_b32 s14, s54
	s_add_u32 s15, s54, s59
	s_min_u32 s16, s14, 0x41ff
	s_lshl_b32 s16, s16, 9
	s_add_u32 s52, s88, s16
	s_addc_u32 s53, s89, 0
	global_load_dword v0, v160, s[52:53]
	global_load_dword v1, v160, s[52:53] offset:256
	s_add_u32 s46, s90, s16
	s_addc_u32 s47, s91, 0
	global_load_dword v2, v160, s[46:47]
	global_load_dword v3, v160, s[46:47] offset:256
	s_add_u32 s52, s92, s16
	s_addc_u32 s53, s93, 0
	global_load_dword v8, v160, s[52:53]
	global_load_dword v9, v160, s[52:53] offset:256
	s_add_u32 s52, s52, 0x840000
	s_addc_u32 s53, s53, 0
	global_load_dword v10, v160, s[52:53]
	global_load_dword v11, v160, s[52:53] offset:256
	s_add_u32 s52, s52, 0x840000
	s_addc_u32 s53, s53, 0
	global_load_dword v12, v160, s[52:53]
	global_load_dword v13, v160, s[52:53] offset:256
	s_add_u32 s52, s52, 0x840000
	s_addc_u32 s53, s53, 0
	global_load_dword v14, v160, s[52:53]
	global_load_dword v15, v160, s[52:53] offset:256
	s_add_u32 s52, s52, 0x840000
	s_addc_u32 s53, s53, 0
	global_load_dword v16, v160, s[52:53]
	global_load_dword v17, v160, s[52:53] offset:256
	s_add_u32 s52, s52, 0x840000
	s_addc_u32 s53, s53, 0
	global_load_dword v18, v160, s[52:53]
	global_load_dword v19, v160, s[52:53] offset:256
	s_add_u32 s52, s52, 0x840000
	s_addc_u32 s53, s53, 0
	global_load_dword v20, v160, s[52:53]
	global_load_dword v21, v160, s[52:53] offset:256
	s_add_u32 s52, s52, 0x840000
	s_addc_u32 s53, s53, 0
	global_load_dword v22, v160, s[52:53]
	global_load_dword v23, v160, s[52:53] offset:256
	s_min_u32 s17, s15, 0x41ff
	s_lshl_b32 s17, s17, 9
	s_add_u32 s52, s88, s17
	s_addc_u32 s53, s89, 0
	global_load_dword v24, v160, s[52:53]
	global_load_dword v25, v160, s[52:53] offset:256
	s_add_u32 s46, s90, s17
	s_addc_u32 s47, s91, 0
	global_load_dword v26, v160, s[46:47]
	global_load_dword v27, v160, s[46:47] offset:256
	s_add_u32 s52, s92, s17
	s_addc_u32 s53, s93, 0
	global_load_dword v32, v160, s[52:53]
	global_load_dword v33, v160, s[52:53] offset:256
	s_add_u32 s52, s52, 0x840000
	s_addc_u32 s53, s53, 0
	global_load_dword v34, v160, s[52:53]
	global_load_dword v35, v160, s[52:53] offset:256
	s_add_u32 s52, s52, 0x840000
	s_addc_u32 s53, s53, 0
	global_load_dword v36, v160, s[52:53]
	global_load_dword v37, v160, s[52:53] offset:256
	s_add_u32 s52, s52, 0x840000
	s_addc_u32 s53, s53, 0
	global_load_dword v38, v160, s[52:53]
	global_load_dword v39, v160, s[52:53] offset:256
	s_add_u32 s52, s52, 0x840000
	s_addc_u32 s53, s53, 0
	global_load_dword v40, v160, s[52:53]
	global_load_dword v41, v160, s[52:53] offset:256
	s_add_u32 s52, s52, 0x840000
	s_addc_u32 s53, s53, 0
	global_load_dword v42, v160, s[52:53]
	global_load_dword v43, v160, s[52:53] offset:256
	s_add_u32 s52, s52, 0x840000
	s_addc_u32 s53, s53, 0
	global_load_dword v44, v160, s[52:53]
	global_load_dword v45, v160, s[52:53] offset:256
	s_add_u32 s52, s52, 0x840000
	s_addc_u32 s53, s53, 0
	global_load_dword v46, v160, s[52:53]
	global_load_dword v47, v160, s[52:53] offset:256
	s_waitcnt vmcnt(18)
	v_lshlrev_b32_e32 v48, 2, v0
	v_lshlrev_b32_e32 v49, 2, v1
	v_lshlrev_b32_e32 v54, 2, v24
	v_lshlrev_b32_e32 v55, 2, v25
	global_load_dword v4, v48, s[44:45]
	global_load_dword v6, v48, s[50:51]
	global_load_dword v5, v49, s[44:45]
	global_load_dword v7, v49, s[50:51]
	global_load_dword v28, v54, s[44:45]
	global_load_dword v30, v54, s[50:51]
	global_load_dword v29, v55, s[44:45]
	global_load_dword v31, v55, s[50:51]
	s_waitcnt vmcnt(8)
	v_add_f32_e32 v8, v8, v10
	v_add_f32_e32 v8, v8, v12
	v_add_f32_e32 v8, v8, v14
	v_add_f32_e32 v8, v8, v16
	v_add_f32_e32 v8, v8, v18
	v_add_f32_e32 v8, v8, v20
	v_add_f32_e32 v8, v8, v22
	v_add_f32_e32 v9, v9, v11
	v_add_f32_e32 v9, v9, v13
	v_add_f32_e32 v9, v9, v15
	v_add_f32_e32 v9, v9, v17
	v_add_f32_e32 v9, v9, v19
	v_add_f32_e32 v9, v9, v21
	v_add_f32_e32 v9, v9, v23
	v_add_f32_e32 v32, v32, v34
	v_add_f32_e32 v32, v32, v36
	v_add_f32_e32 v32, v32, v38
	v_add_f32_e32 v32, v32, v40
	v_add_f32_e32 v32, v32, v42
	v_add_f32_e32 v32, v32, v44
	v_add_f32_e32 v32, v32, v46
	v_add_f32_e32 v33, v33, v35
	v_add_f32_e32 v33, v33, v37
	v_add_f32_e32 v33, v33, v39
	v_add_f32_e32 v33, v33, v41
	v_add_f32_e32 v33, v33, v43
	v_add_f32_e32 v33, v33, v45
	v_add_f32_e32 v33, v33, v47
	s_waitcnt vmcnt(0)
	v_mul_f32_e32 v50, v4, v8
	v_mul_f32_e32 v51, 0x3d372713, v50
	v_mul_f32_e32 v51, v50, v51
	v_fma_f32 v51, v50, v51, v50
	v_mul_f32_e32 v51, 0x3f4c422a, v51
	v_mul_f32_e32 v51, -2.0, v51
	v_mul_f32_e32 v51, 0x3fb8aa3b, v51
	v_exp_f32_e32 v51, v51
	v_mul_f32_e32 v2, v2, v6
	v_add_f32_e32 v51, 1.0, v51
	v_rcp_f32_e32 v51, v51
	s_nop 0
	v_mul_f32_e32 v50, v50, v51
	v_mul_f32_e32 v2, v2, v50
	v_mul_f32_e32 v52, v5, v9
	v_mul_f32_e32 v53, 0x3d372713, v52
	v_mul_f32_e32 v53, v52, v53
	v_fma_f32 v53, v52, v53, v52
	v_mul_f32_e32 v53, 0x3f4c422a, v53
	v_mul_f32_e32 v53, -2.0, v53
	v_mul_f32_e32 v53, 0x3fb8aa3b, v53
	v_exp_f32_e32 v53, v53
	v_mul_f32_e32 v3, v3, v7
	v_add_f32_e32 v53, 1.0, v53
	v_rcp_f32_e32 v53, v53
	s_nop 0
	v_mul_f32_e32 v52, v52, v53
	v_mul_f32_e32 v3, v3, v52
	v_mul_f32_e32 v56, v28, v32
	v_mul_f32_e32 v57, 0x3d372713, v56
	v_mul_f32_e32 v57, v56, v57
	v_fma_f32 v57, v56, v57, v56
	v_mul_f32_e32 v57, 0x3f4c422a, v57
	v_mul_f32_e32 v57, -2.0, v57
	v_mul_f32_e32 v57, 0x3fb8aa3b, v57
	v_exp_f32_e32 v57, v57
	v_mul_f32_e32 v26, v26, v30
	v_add_f32_e32 v57, 1.0, v57
	v_rcp_f32_e32 v57, v57
	s_nop 0
	v_mul_f32_e32 v56, v56, v57
	v_mul_f32_e32 v26, v26, v56
	v_mul_f32_e32 v58, v29, v33
	v_mul_f32_e32 v59, 0x3d372713, v58
	v_mul_f32_e32 v59, v58, v59
	v_fma_f32 v59, v58, v59, v58
	v_mul_f32_e32 v59, 0x3f4c422a, v59
	v_mul_f32_e32 v59, -2.0, v59
	v_mul_f32_e32 v59, 0x3fb8aa3b, v59
	v_exp_f32_e32 v59, v59
	v_mul_f32_e32 v27, v27, v31
	v_add_f32_e32 v59, 1.0, v59
	v_rcp_f32_e32 v59, v59
	s_nop 0
	v_mul_f32_e32 v58, v58, v59
	v_mul_f32_e32 v27, v27, v58
	s_add_u32 s46, s92, s16
	s_addc_u32 s47, s93, 0
	s_add_u32 s46, s46, 0x5000000
	s_addc_u32 s47, s47, 0
	global_store_dword v160, v2, s[46:47]
	global_store_dword v160, v3, s[46:47] offset:256
	s_cmp_lt_u32 s15, 0x4200
	s_cbranch_scc0 .Lgy_Bskip_11
	s_add_u32 s46, s92, s17
	s_addc_u32 s47, s93, 0
	s_add_u32 s46, s46, 0x5000000
	s_addc_u32 s47, s47, 0
	global_store_dword v160, v26, s[46:47]
	global_store_dword v160, v27, s[46:47] offset:256
.Lgy_Bskip_11:
	s_add_u32 s54, s15, s59
	s_cmp_lt_u32 s54, 0x4200
	s_cbranch_scc1 .Lgy_Btok_8
